# post1 token loop: 12 loop-invariant gain loads read once before the loop (each was load + vmcnt(0) incl. store drain per use)
# speedup vs baseline: 1.0174x; 1.0115x over previous
.LBB0_600:
	s_andn2_b64 vcc, exec, s[0:1]
	s_cbranch_vccnz .LBB0_669
	v_readlane_b32 s0, v254, 3
	v_readlane_b32 s1, v254, 4
	v_mov_b32_e32 v3, v206
	s_andn2_b64 vcc, exec, s[0:1]
	s_cbranch_vccnz .LBB0_660
	v_ashrrev_i32_e32 v38, 6, v3
	v_lshlrev_b32_e32 v0, 1, v38
	v_and_b32_e32 v53, 8, v0
	v_and_b32_e32 v0, 15, v3
	v_cvt_f32_ubyte0_e32 v0, v0
	v_mul_f32_e32 v4, 0xbf549a78, v0
	s_mov_b32 s0, 0xc2fc0000
	v_readlane_b32 s4, v254, 53
	v_cmp_gt_f32_e32 vcc, s0, v4
	v_mov_b32_e32 v4, 0x42800000
	v_readlane_b32 s5, v254, 54
	v_cndmask_b32_e32 v4, 0, v4, vcc
	v_fmac_f32_e32 v4, 0xbf549a78, v0
	s_and_b64 s[0:1], s[4:5], exec
	v_and_b32_e32 v2, 63, v3
	v_exp_f32_e32 v0, v4
	s_cselect_b32 s0, 64, 0
	v_or_b32_e32 v26, s0, v2
	s_cselect_b32 s0, 0x180, 0
	v_not_b32_e32 v4, 63
	v_or_b32_e32 v30, s0, v2
	s_cselect_b32 s0, 0x80, 0
	v_cndmask_b32_e32 v4, 0, v4, vcc
	v_or_b32_e32 v32, s0, v2
	v_readlane_b32 s0, v254, 17
	v_ldexp_f32 v54, v0, v4
	v_lshlrev_b32_e32 v0, 2, v2
	v_readlane_b32 s1, v254, 18
	v_readlane_b32 s36, v252, 1
	v_and_b32_e32 v8, 16, v3
	v_lshl_add_u64 v[4:5], s[0:1], 0, v[0:1]
	v_readlane_b32 s0, v254, 15
	v_readlane_b32 s37, v252, 2
	v_readlane_b32 s38, v252, 3
	v_readlane_b32 s39, v252, 4
	v_readlane_b32 s40, v252, 5
	v_readlane_b32 s41, v252, 6
	v_readlane_b32 s42, v252, 7
	v_readlane_b32 s43, v252, 8
	v_readlane_b32 s44, v252, 9
	v_readlane_b32 s45, v252, 10
	v_readlane_b32 s46, v252, 11
	v_readlane_b32 s47, v252, 12
	v_readlane_b32 s48, v252, 13
	v_readlane_b32 s49, v252, 14
	v_readlane_b32 s50, v252, 15
	v_readlane_b32 s51, v252, 16
	v_cndmask_b32_e64 v52, 0, 1, s[4:5]
	v_readlane_b32 s1, v254, 16
	v_cmp_eq_u32_e64 s[4:5], 0, v8
	v_lshl_add_u64 v[8:9], s[44:45], 0, v[0:1]
	v_lshl_add_u64 v[10:11], s[46:47], 0, v[0:1]
	v_readlane_b32 s36, v253, 17
	v_lshl_add_u64 v[6:7], s[0:1], 0, v[0:1]
	v_lshlrev_b32_e32 v0, 1, v2
	v_readlane_b32 s37, v253, 18
	v_readlane_b32 s38, v253, 19
	v_readlane_b32 s39, v253, 20
	v_readlane_b32 s40, v253, 21
	v_readlane_b32 s41, v253, 22
	v_readlane_b32 s42, v253, 23
	v_readlane_b32 s43, v253, 24
	v_readlane_b32 s44, v253, 25
	v_readlane_b32 s45, v253, 26
	v_readlane_b32 s46, v253, 27
	v_readlane_b32 s47, v253, 28
	v_readlane_b32 s48, v253, 29
	v_readlane_b32 s49, v253, 30
	v_readlane_b32 s50, v253, 31
	v_readlane_b32 s51, v253, 32
	s_waitcnt vmcnt(0)
	v_lshl_add_u64 v[14:15], s[46:47], 0, v[0:1]
	v_lshl_add_u64 v[16:17], s[48:49], 0, v[0:1]
	v_lshl_add_u64 v[18:19], s[40:41], 0, v[0:1]
	v_lshl_add_u64 v[22:23], s[44:45], 0, v[0:1]
	v_lshl_add_u64 v[24:25], s[38:39], 0, v[0:1]
	v_readlane_b32 s36, v252, 17
	v_lshl_add_u64 v[12:13], s[94:95], 0, v[0:1]
	v_lshl_add_u64 v[20:21], s[90:91], 0, v[0:1]
	v_lshlrev_b32_e32 v0, 2, v26
	v_readlane_b32 s37, v252, 18
	v_readlane_b32 s38, v252, 19
	v_readlane_b32 s39, v252, 20
	v_readlane_b32 s40, v252, 21
	v_readlane_b32 s41, v252, 22
	v_readlane_b32 s42, v252, 23
	v_readlane_b32 s43, v252, 24
	v_readlane_b32 s44, v252, 25
	v_readlane_b32 s45, v252, 26
	v_readlane_b32 s46, v252, 27
	v_readlane_b32 s47, v252, 28
	v_readlane_b32 s48, v252, 29
	v_readlane_b32 s49, v252, 30
	v_readlane_b32 s50, v252, 31
	v_readlane_b32 s51, v252, 32
	v_lshlrev_b32_e32 v30, 2, v30
	v_mov_b32_e32 v31, v1
	v_lshl_add_u64 v[26:27], s[50:51], 0, v[0:1]
	v_readlane_b32 s36, v252, 33
	v_readlane_b32 s37, v252, 34
	v_readlane_b32 s38, v252, 35
	v_readlane_b32 s39, v252, 36
	v_readlane_b32 s40, v252, 37
	v_readlane_b32 s41, v252, 38
	v_readlane_b32 s42, v252, 39
	v_readlane_b32 s43, v252, 40
	v_readlane_b32 s44, v252, 41
	v_readlane_b32 s45, v252, 42
	v_readlane_b32 s46, v252, 43
	v_readlane_b32 s47, v252, 44
	v_readlane_b32 s48, v252, 45
	v_readlane_b32 s49, v252, 46
	v_readlane_b32 s50, v252, 47
	v_readlane_b32 s51, v252, 48
	v_lshlrev_b32_e32 v32, 2, v32
	v_mov_b32_e32 v33, v1
	v_lshl_add_u64 v[28:29], s[36:37], 0, v[0:1]
	v_lshl_add_u64 v[30:31], s[40:41], 0, v[30:31]
	v_lshl_add_u64 v[32:33], s[44:45], 0, v[32:33]
	v_readlane_b32 s36, v252, 49
	v_readlane_b32 s37, v252, 50
	v_readlane_b32 s38, v252, 51
	v_readlane_b32 s39, v252, 52
	v_readlane_b32 s0, v254, 42
	v_cmp_gt_u32_e32 vcc, 32, v2
	v_mul_u32_u24_e32 v55, 0x3800, v2
	v_lshl_add_u64 v[34:35], s[36:37], 0, v[0:1]
	v_lshl_add_u64 v[36:37], s[38:39], 0, v[0:1]
	v_add_u32_e32 v38, s0, v38
	v_readlane_b32 s52, v252, 0
	v_readlane_b32 s40, v252, 53
	v_readlane_b32 s41, v252, 54
	v_readlane_b32 s42, v252, 55
	v_readlane_b32 s43, v252, 56
	v_readlane_b32 s44, v252, 57
	v_readlane_b32 s45, v252, 58
	v_readlane_b32 s46, v252, 59
	v_readlane_b32 s47, v252, 60
	v_readlane_b32 s48, v252, 61
	v_readlane_b32 s49, v252, 62
	v_readlane_b32 s50, v252, 63
	v_readlane_b32 s51, v253, 0
	global_load_dword v108, v[26:27], off
	global_load_dword v109, v[28:29], off
	global_load_dword v110, v[30:31], off
	global_load_dword v111, v[30:31], off offset:256
	global_load_dword v112, v[30:31], off offset:512
	global_load_dword v113, v[30:31], off offset:768
	global_load_dword v114, v[30:31], off offset:1024
	global_load_dword v115, v[30:31], off offset:1280
	global_load_dword v116, v[32:33], off
	global_load_dword v117, v[32:33], off offset:256
	global_load_dword v118, v[34:35], off
	global_load_dword v119, v[36:37], off
	s_waitcnt vmcnt(0)
	s_branch .LBB0_605

.LBB0_614:
	s_or_saveexec_b64 s[0:1], s[76:77]
	v_mov_b64_e32 v[40:41], 0
	s_xor_b64 exec, exec, s[0:1]
	v_ashrrev_i32_e32 v0, 7, v38
	v_and_or_b32 v40, v0, -2, v52
	v_ashrrev_i32_e32 v41, 31, v40
	v_lshlrev_b64 v[40:41], 8, v[40:41]
	s_movk_i32 s10, 0xff
	v_and_or_b32 v40, v38, s10, v40
	v_mov_b32_e32 v0, 1.0
	v_mov_b32_e32 v60, 0
	s_or_b64 exec, exec, s[0:1]
	v_mov_b32_e32 v91, v108
	v_mov_b32_e32 v89, v109
	s_waitcnt vmcnt(0)
	v_lshlrev_b32_e32 v44, 16, v44
	v_mul_f32_e32 v45, v44, v44
	v_mov_b32_e32 v46, v1
	s_mov_b32 s1, 0x800000
	v_ashrrev_i32_e32 v39, 31, v38
	v_mov_b32_dpp v46, v45 quad_perm:[1,0,3,2] row_mask:0xf bank_mask:0xf
	v_fmac_f32_e32 v46, v44, v44
	v_lshlrev_b32_e32 v102, 16, v102
	v_mov_b32_e32 v104, v1
	v_add_f32_dpp v45, v46, v46 quad_perm:[2,3,0,1] row_mask:0xf bank_mask:0xf bound_ctrl:1
	v_mov_b32_e32 v46, v1
	v_lshlrev_b64 v[42:43], 9, v[40:41]
	v_add_f32_dpp v45, v45, v45 row_half_mirror row_mask:0xf bank_mask:0xf bound_ctrl:1
	v_or_b32_e32 v50, v42, v2
	v_mov_b32_e32 v51, v43
	v_add_f32_dpp v45, v45, v45 row_mirror row_mask:0xf bank_mask:0xf bound_ctrl:1
	v_lshlrev_b64 v[50:51], 2, v[50:51]
	s_nop 0
	v_mov_b32_dpp v46, v45 row_bcast:15 row_mask:0xa bank_mask:0xf
	v_add_f32_e32 v45, v45, v46
	v_mov_b32_e32 v46, v1
	s_nop 1
	v_mov_b32_dpp v46, v45 row_bcast:31 row_mask:0xc bank_mask:0xf
	v_add_f32_e32 v45, v45, v46
	s_nop 0
	v_readlane_b32 s0, v45, 63
	s_nop 1
	v_fma_f32 v45, s0, v208, v209
	v_cmp_gt_f32_e64 s[10:11], s1, v45
	v_mul_f32_e32 v46, 0x4b800000, v45
	s_nop 0
	v_cndmask_b32_e64 v45, v45, v46, s[10:11]
	v_rsq_f32_e32 v45, v45
	s_nop 0
	v_mul_f32_e32 v46, 0x45800000, v45
	v_cndmask_b32_e64 v45, v45, v46, s[10:11]
	v_mul_f32_e32 v44, v45, v44
	v_mul_f32_e32 v44, v91, v44
	v_mul_f32_e32 v44, 0x3e38aa3b, v44
	v_cvt_pk_bf16_f32 v103, v44, s0
	v_lshlrev_b64 v[44:45], 10, v[38:39]
	v_lshl_or_b32 v48, v2, 1, v44
	v_mov_b32_e32 v49, v45
	v_lshl_add_u64 v[46:47], s[92:93], 0, v[48:49]
	global_store_short v[46:47], v103, off
	v_mul_f32_e32 v103, v102, v102
	v_lshl_add_u64 v[48:49], s[94:95], 0, v[48:49]
	s_nop 0
	v_mov_b32_dpp v104, v103 quad_perm:[1,0,3,2] row_mask:0xf bank_mask:0xf
	v_fmac_f32_e32 v104, v102, v102
	s_nop 1
	v_add_f32_dpp v103, v104, v104 quad_perm:[2,3,0,1] row_mask:0xf bank_mask:0xf bound_ctrl:1
	v_mov_b32_e32 v104, v1
	s_nop 0
	v_add_f32_dpp v103, v103, v103 row_half_mirror row_mask:0xf bank_mask:0xf bound_ctrl:1
	s_nop 1
	v_add_f32_dpp v103, v103, v103 row_mirror row_mask:0xf bank_mask:0xf bound_ctrl:1
	s_nop 1
	v_mov_b32_dpp v104, v103 row_bcast:15 row_mask:0xa bank_mask:0xf
	v_add_f32_e32 v103, v103, v104
	v_mov_b32_e32 v104, v1
	s_nop 1
	v_mov_b32_dpp v104, v103 row_bcast:31 row_mask:0xc bank_mask:0xf
	v_add_f32_e32 v103, v103, v104
	s_nop 0
	v_readlane_b32 s0, v103, 63
	s_nop 1
	v_fma_f32 v103, s0, v208, v209
	v_cmp_gt_f32_e64 s[10:11], s1, v103
	v_mul_f32_e32 v104, 0x4b800000, v103
	s_nop 0
	v_cndmask_b32_e64 v103, v103, v104, s[10:11]
	v_rsq_f32_e32 v103, v103
	s_nop 0
	v_mul_f32_e32 v104, 0x45800000, v103
	v_cndmask_b32_e64 v103, v103, v104, s[10:11]
	v_mul_f32_e32 v102, v103, v102
	v_mul_f32_e32 v102, v89, v102
	v_cvt_pk_bf16_f32 v103, v102, s0
	global_store_short v[48:49], v103, off
	s_and_saveexec_b64 s[0:1], s[8:9]
	s_cbranch_execz .LBB0_618
	v_readlane_b32 s10, v254, 7
	v_readlane_b32 s11, v254, 8
	v_lshlrev_b32_e32 v101, 16, v101
	s_nop 0
	v_lshl_add_u64 v[104:105], s[10:11], 0, v[50:51]
	v_readlane_b32 s10, v254, 9
	v_readlane_b32 s11, v254, 10
	s_nop 1
	v_lshl_add_u64 v[106:107], s[10:11], 0, v[50:51]
	global_store_dword v[104:105], v102, off
	global_store_dword v[106:107], v101, off

.LBB0_632:
	s_or_b64 exec, exec, s[0:1]
	v_lshlrev_b32_e32 v77, 16, v77
	v_lshlrev_b32_e32 v76, 16, v76
	v_mul_f32_e32 v50, v77, v77
	v_lshlrev_b32_e32 v49, 16, v75
	v_lshlrev_b32_e32 v48, 16, v74
	v_fmac_f32_e32 v50, v76, v76
	v_pk_mul_f32 v[46:47], v[48:49], v[48:49]
	s_mov_b32 s10, 0x800000
	v_add_f32_e32 v46, v50, v46
	v_add_f32_e32 v74, v46, v47
	v_lshlrev_b32_e32 v47, 16, v73
	v_lshlrev_b32_e32 v46, 16, v72
	v_pk_mul_f32 v[50:51], v[46:47], v[46:47]
	s_nop 0
	v_add_f32_e32 v50, v74, v50
	v_mov_b32_e32 v74, v110
	v_add_f32_e32 v50, v50, v51
	v_mov_b32_e32 v51, v1
	s_nop 0
	v_add_f32_dpp v50, v50, v50 quad_perm:[1,0,3,2] row_mask:0xf bank_mask:0xf bound_ctrl:1
	s_nop 1
	v_add_f32_dpp v50, v50, v50 quad_perm:[2,3,0,1] row_mask:0xf bank_mask:0xf bound_ctrl:1
	s_nop 1
	v_add_f32_dpp v50, v50, v50 row_half_mirror row_mask:0xf bank_mask:0xf bound_ctrl:1
	s_nop 1
	v_add_f32_dpp v50, v50, v50 row_mirror row_mask:0xf bank_mask:0xf bound_ctrl:1
	s_nop 1
	v_mov_b32_dpp v51, v50 row_bcast:15 row_mask:0xa bank_mask:0xf
	v_add_f32_e32 v50, v50, v51
	v_mov_b32_e32 v51, v1
	s_nop 1
	v_mov_b32_dpp v51, v50 row_bcast:31 row_mask:0xc bank_mask:0xf
	v_add_f32_e32 v50, v50, v51
	s_nop 0
	v_readlane_b32 s0, v50, 63
	v_mov_b32_e32 v50, 0x3b2aaaab
	s_nop 0
	v_fma_f32 v50, s0, v50, v209
	v_cmp_gt_f32_e64 s[8:9], s10, v50
	v_mul_f32_e32 v51, 0x4b800000, v50
	s_movk_i32 s0, 0x300
	v_cndmask_b32_e64 v50, v50, v51, s[8:9]
	v_rsq_f32_e32 v50, v50
	s_nop 0
	v_mul_f32_e32 v51, 0x45800000, v50
	v_cndmask_b32_e64 v72, v50, v51, s[8:9]
	v_mul_f32_e32 v73, v72, v76
	v_mad_i64_i32 v[50:51], s[0:1], v38, s0, v[22:23]
	v_mul_f32_e32 v48, v72, v48
	v_mul_f32_e32 v46, v72, v46
	v_mul_f32_e32 v73, v74, v73
	v_mov_b32_e32 v74, v111
	v_cvt_pk_bf16_f32 v73, v73, s0
	global_store_short v[50:51], v73, off
	v_mul_f32_e32 v73, v72, v77
	v_mul_f32_e32 v73, v74, v73
	v_cvt_pk_bf16_f32 v73, v73, s0
	global_store_short v[50:51], v73, off offset:128
	v_mov_b32_e32 v73, v112
	v_mul_f32_e32 v48, v73, v48
	v_cvt_pk_bf16_f32 v48, v48, s0
	global_store_short v[50:51], v48, off offset:256
	v_mul_f32_e32 v48, v72, v49
	v_mov_b32_e32 v49, v113
	v_mul_f32_e32 v48, v49, v48
	v_cvt_pk_bf16_f32 v48, v48, s0
	global_store_short v[50:51], v48, off offset:384
	v_mov_b32_e32 v48, v114
	v_mul_f32_e32 v46, v46, v48
	v_cvt_pk_bf16_f32 v46, v46, s0
	global_store_short v[50:51], v46, off offset:512
	v_mul_f32_e32 v46, v72, v47
	v_mov_b32_e32 v47, v115
	v_mul_f32_e32 v46, v46, v47
	v_cvt_pk_bf16_f32 v46, v46, s0
	global_store_short v[50:51], v46, off offset:640
	v_lshlrev_b32_e32 v47, 16, v71
	v_lshlrev_b32_e32 v46, 16, v70
	v_pk_mul_f32 v[48:49], v[46:47], v[46:47]
	s_nop 0
	v_add_f32_e32 v48, v48, v49
	v_mov_b32_e32 v49, v1
	s_nop 0
	v_add_f32_dpp v48, v48, v48 quad_perm:[1,0,3,2] row_mask:0xf bank_mask:0xf bound_ctrl:1
	s_nop 1
	v_add_f32_dpp v48, v48, v48 quad_perm:[2,3,0,1] row_mask:0xf bank_mask:0xf bound_ctrl:1
	s_nop 1
	v_add_f32_dpp v48, v48, v48 row_half_mirror row_mask:0xf bank_mask:0xf bound_ctrl:1
	s_nop 1
	v_add_f32_dpp v48, v48, v48 row_mirror row_mask:0xf bank_mask:0xf bound_ctrl:1
	s_nop 1
	v_mov_b32_dpp v49, v48 row_bcast:15 row_mask:0xa bank_mask:0xf
	v_add_f32_e32 v48, v48, v49
	v_mov_b32_e32 v49, v1
	s_nop 1
	v_mov_b32_dpp v49, v48 row_bcast:31 row_mask:0xc bank_mask:0xf
	v_add_f32_e32 v48, v48, v49
	s_nop 0
	v_readlane_b32 s0, v48, 63
	v_bfrev_b32_e32 v48, 60
	s_nop 0
	v_fma_f32 v48, s0, v48, v209
	v_cmp_gt_f32_e64 s[8:9], s10, v48
	v_mul_f32_e32 v49, 0x4b800000, v48
	s_nop 0
	v_cndmask_b32_e64 v48, v48, v49, s[8:9]
	v_rsq_f32_e32 v48, v48
	s_nop 0
	v_mul_f32_e32 v49, 0x45800000, v48
	v_cndmask_b32_e64 v48, v48, v49, s[8:9]
	v_mov_b32_e32 v49, v116
	v_mul_f32_e32 v46, v48, v46
	v_mul_f32_e32 v50, v49, v46
	v_mul_f32_e32 v46, v48, v47
	v_mov_b32_e32 v47, v117
	v_lshlrev_b64 v[48:49], 8, v[38:39]
	v_cvt_pk_bf16_f32 v70, v50, s0
	v_lshl_add_u64 v[48:49], v[14:15], 0, v[48:49]
	global_store_short v[48:49], v70, off
	v_mul_f32_e32 v51, v47, v46
	v_lshlrev_b64 v[46:47], 7, v[38:39]
	v_cvt_pk_bf16_f32 v39, v51, s0
	global_store_short v[48:49], v39, off offset:128
	v_lshl_add_u64 v[48:49], v[16:17], 0, v[46:47]
	s_and_saveexec_b64 s[0:1], s[6:7]
	s_xor_b64 s[0:1], exec, s[0:1]
	s_cbranch_execz .LBB0_634
	global_store_short v[48:49], v69, off

.LBB0_636:
	s_or_b64 exec, exec, s[0:1]
	v_mov_b32_e32 v48, v118
	v_mov_b32_e32 v39, v119
	v_lshlrev_b32_e32 v42, 16, v68
	v_mul_f32_e32 v43, v42, v42
	v_mov_b32_e32 v49, v1
	s_nop 1
	v_mov_b32_dpp v49, v43 quad_perm:[1,0,3,2] row_mask:0xf bank_mask:0xf
	v_fmac_f32_e32 v49, v42, v42
	s_nop 1
	v_add_f32_dpp v43, v49, v49 quad_perm:[2,3,0,1] row_mask:0xf bank_mask:0xf bound_ctrl:1
	v_mov_b32_e32 v49, v1
	s_nop 0
	v_add_f32_dpp v43, v43, v43 row_half_mirror row_mask:0xf bank_mask:0xf bound_ctrl:1
	s_nop 1
	v_add_f32_dpp v43, v43, v43 row_mirror row_mask:0xf bank_mask:0xf bound_ctrl:1
	s_nop 1
	v_mov_b32_dpp v49, v43 row_bcast:15 row_mask:0xa bank_mask:0xf
	v_add_f32_e32 v43, v43, v49
	v_mov_b32_e32 v49, v1
	s_nop 1
	v_mov_b32_dpp v49, v43 row_bcast:31 row_mask:0xc bank_mask:0xf
	v_add_f32_e32 v43, v43, v49
	s_nop 0
	v_readlane_b32 s0, v43, 63
	s_nop 1
	v_fma_f32 v43, s0, v208, v209
	s_mov_b32 s0, 0x800000
	v_mul_f32_e32 v49, 0x4b800000, v43
	v_cmp_gt_f32_e64 s[8:9], s0, v43
	s_nop 1
	v_cndmask_b32_e64 v43, v43, v49, s[8:9]
	v_rsq_f32_e32 v43, v43
	s_nop 0
	v_mul_f32_e32 v49, 0x45800000, v43
	v_cndmask_b32_e64 v43, v43, v49, s[8:9]
	v_mul_f32_e32 v42, v43, v42
	v_mul_f32_e32 v49, v48, v42
	s_and_saveexec_b64 s[0:1], s[6:7]
	s_cbranch_execz .LBB0_638
	v_and_b32_e32 v43, 64, v221
	v_xor_b32_e32 v42, 16, v221
	v_add_u32_e32 v43, 64, v43
	v_cmp_lt_i32_e64 s[8:9], v42, v43
	s_nop 1
	v_cndmask_b32_e64 v42, v221, v42, s[8:9]
	v_lshlrev_b32_e32 v42, 2, v42
	ds_bpermute_b32 v42, v42, v49
	s_waitcnt lgkmcnt(0)
	v_mul_f32_e32 v42, v60, v42
	v_cndmask_b32_e64 v42, v42, -v42, s[4:5]
	v_fmac_f32_e32 v42, v0, v49
	v_mov_b32_e32 v49, v42
